# six XCD-local seams (no L2 write-back, no cross-XCD rendezvous) behind a runtime check that every logical tile-owner group sits on one XCC; global seam otherwise
# speedup vs baseline: 1.0325x; 1.0206x over previous
; #define LAS __attribute__((address_space(3)))
; __device__ __forceinline__ unsigned xb_add(unsigned* p, unsigned v) { return __hip_atomic_fetch_add(p, v, __ATOMIC_RELAXED, __HIP_MEMORY_SCOPE_AGENT); }
; __device__ __forceinline__ unsigned xb_xcc_id() { return (unsigned)__builtin_amdgcn_s_getreg((3 << 11) | 20) & 0xFu; }
; __device__ __forceinline__ XcdBarrier xcd_barrier_post(unsigned* bar, volatile LAS unsigned* st) {
;     XcdBarrier b; b.bar = bar; b.x = xb_xcc_id(); b.st = st;
;     if (threadIdx.x == 0) (void)xb_add(&bar[XB_XCNT(b.x)], 1u);
;     return b;
; }
.LBB0_5:
	s_or_b64 exec, exec, s[4:5]
	s_and_saveexec_b64 s[4:5], s[14:15]
	s_cbranch_execz .Lxcdchk_done
	s_and_b32 s3, s2, 7
	s_lshl_b32 s3, s3, 2
	s_add_i32 s3, s3, 0x3800
	s_lshl_b32 s8, 1, s93
	v_mov_b32_e32 v1, s3
	v_mov_b32_e32 v2, s8
	global_atomic_or v1, v2, s[94:95]

; #define PG8_STAGE(bufoff, gbase, voff) do { _Pragma("unroll") for (int _i = 0; _i < 2; ++_i) \
;         __builtin_amdgcn_global_load_lds((const unsigned*)((const char*)(gbase) + (voff)[_i]), (PG8_LAS unsigned*)(lds + (bufoff) + ldsw + _i * 8192), 16, 0, 0); } while (0)
; template <class Epi, class Sched, bool ALIGN_EPI = false, bool SP2 = false>
; __device__ __forceinline__ void gemm_phase(PG8_LAS unsigned char* lds, const Gemm g, const Sched& S, const Epi& E) {
;     ...
;     for (int i = 0; i < 2; ++i) { int R, C; stage_rc(tid * 16 + i * 8192, R, C); const int Rb = Epi::PERM ? ((R & ~31) + perm32(R & 31)) : R;
;         voffA[i] = (unsigned)(R * K + C) * 2u; voffB[i] = (unsigned)(Rb * K + C) * 2u; }
;     const size_t kstep = (size_t)(BK * 2);
;     const size_t hstep = (size_t)HALF * K * 2;
;     const size_t tstep = 2 * hstep;
;     const unsigned ldsw = (unsigned)wid * 1024u;
;     const int aoff = lds_byte(wr * 64 + fr, fq * 8), boff = lds_byte(wc * 32 + fr, fq * 8);
;     ...
;     Unit cur, nxt; int ui = 0;
;     if (!S.next(0, cur)) return;
;     f32x4 acc[2][2][4][2];
; #pragma unroll
;     for (int a = 0; a < 2; ++a)
; #pragma unroll
;         for (int b = 0; b < 2; ++b)
; #pragma unroll
;             for (int m = 0; m < 4; ++m)
; #pragma unroll
;                 for (int n = 0; n < 2; ++n) acc[a][b][m][n] = (f32x4){0.f, 0.f, 0.f, 0.f};
;     bf16x8 At[4][2], B0[2][2], B1[2][2];
;     const char* cA = (const char*)g.A + (size_t)cur.pm * tstep; const char* cB = (const char*)g.Bt + (size_t)cur.pn * tstep;
;     S.a_ready(cur);
;     if constexpr (SP2) {
;         PG8_STAGE(PG8_SB(0, 0), cB, voffB); PG8_STAGE(PG8_SB(0, 1), cB + hstep, voffB); PG8_STAGE(PG8_SA(0, 0), cA, voffA); PG8_STAGE(PG8_SA(0, 1), cA + hstep, voffA);
.LBB0_196:
	v_lshlrev_b32_e32 v0, 2, v196
	v_and_b32_e32 v0, 28, v0
	v_add_u32_e32 v0, 0x3800, v0
	s_add_u32 s98, s28, 0x180000
	s_addc_u32 s99, s29, 0
	global_load_dword v1, v0, s[98:99] sc1
	s_and_b32 s100, s22, 7
	s_waitcnt vmcnt(0)
	v_bcnt_u32_b32 v1, v1, 0
	v_cmp_ne_u32_e32 vcc, 1, v1
	s_nop 3
	s_cmp_eq_u64 vcc, 0
	s_cselect_b32 s98, 1, 0
	s_cmp_eq_u32 s100, 0
	s_cselect_b32 s98, s98, 0
	v_writelane_b32 v249, s98, 48
	s_cmp_lt_i32 s30, 2
	s_cselect_b64 s[4:5], -1, 0
	s_add_u32 s36, s28, 0x6800000
	s_addc_u32 s37, s29, 0
	s_add_u32 s40, s28, 0xa800000
	s_addc_u32 s41, s29, 0
	s_and_b64 s[6:7], s[4:5], s[0:1]
	s_andn2_b64 vcc, exec, s[6:7]
	s_cbranch_vccnz .LBB0_231
	s_ashr_i32 s3, s2, 31
	s_cmpk_lt_i32 s2, 0xb00
	s_cbranch_scc0 .Lpro_skip_0
	v_readfirstlane_b32 s5, v197
	s_nop 3
	v_lshrrev_b32_e32 v0, 5, v197
	v_lshrrev_b32_e32 v2, 1, v197
	v_and_b32_e32 v0, 4, v0
	v_bfe_u32 v1, v197, 2, 2
	v_and_b32_e32 v11, 24, v2
	v_or3_b32 v0, v0, v1, v11
	v_lshlrev_b32_e32 v1, 4, v197
	v_add_u32_e32 v8, 0x2000, v1
	v_lshrrev_b32_e32 v2, 7, v8
	s_movk_i32 s0, 0xe0
	v_and_b32_e32 v4, 32, v197
	v_and_or_b32 v3, v2, s0, v0
	v_bitop3_b32 v9, v1, v4, 48 bitop3:0x6c
	v_and_b32_e32 v10, 64, v197
	v_bfe_u32 v12, v197, 2, 4
	s_movk_i32 s0, 0xf0
	v_or_b32_e32 v1, v9, v10
	v_and_or_b32 v2, v2, s0, v12
	v_lshl_or_b32 v130, v2, 11, v1
	v_lshrrev_b32_e32 v2, 3, v197
	s_movk_i32 s0, 0x60
	s_add_u32 s53, s28, 0x800000
	v_and_or_b32 v0, v2, s0, v0
	s_movk_i32 s0, 0x70
	s_addc_u32 s54, s29, 0
	v_lshl_or_b32 v132, v0, 11, v1
	v_and_or_b32 v0, v2, s0, v12
	s_lshr_b32 s0, s3, 29
	s_add_i32 s0, s2, s0
	s_lshr_b32 s8, s5, 6
	s_ashr_i32 s1, s0, 3
	s_and_b32 s0, s0, -8
	s_lshr_b32 s12, s5, 8
	s_lshl_b32 s55, s8, 10
	s_sub_i32 s0, s2, s0
	s_cmp_lt_i32 s0, 0
	s_movk_i32 s56, 0x161
	s_cselect_b32 s4, s56, 0x160
	s_mul_i32 s0, s4, s0
	s_add_i32 s0, s0, s1
	s_mul_hi_i32 s1, s0, 0x2e8ba2e9
	s_lshr_b32 s4, s1, 31
	s_ashr_i32 s1, s1, 5
	s_add_i32 s1, s1, s4
	s_lshl_b32 s9, s1, 3
	s_mulk_i32 s1, 0xb0
	s_sub_i32 s0, s0, s1
	s_sext_i32_i16 s1, s0
	s_bfe_u32 s1, s1, 0x3001c
	s_add_i32 s1, s0, s1
	s_sext_i32_i16 s4, s1
	s_and_b32 s1, s1, 0xfff8
	s_sub_i32 s0, s0, s1
	s_sext_i32_i16 s0, s0
	s_lshr_b32 s4, s4, 3
	s_add_i32 s34, s9, s0
	s_ashr_i32 s35, s34, 31
	s_bfe_i64 s[10:11], s[4:5], 0x100000
	s_lshl_b64 s[0:1], s[34:35], 19
	s_lshl_b64 s[10:11], s[10:11], 19
	s_add_u32 s42, s53, s10
	s_addc_u32 s43, s54, s11
	s_add_i32 s35, s55, 0
	s_add_i32 m0, s35, 0x10000
	v_lshl_or_b32 v128, v3, 11, v1
	global_load_lds_dwordx4 v132, s[42:43]
	s_add_i32 m0, s35, 0x12000
	s_add_u32 s10, s42, 0x40000
	global_load_lds_dwordx4 v128, s[42:43]
	s_addc_u32 s11, s43, 0
	s_add_i32 m0, s35, 0x14000
	v_lshl_or_b32 v134, v0, 11, v1
	global_load_lds_dwordx4 v132, s[10:11]
	s_add_i32 m0, s35, 0x16000
	s_add_u32 s20, s36, s0
	s_addc_u32 s21, s37, s1
	s_add_i32 s57, s35, 0x2000
	global_load_lds_dwordx4 v128, s[10:11]
	s_mov_b32 m0, s35
	s_add_u32 s0, s20, 0x40000
	global_load_lds_dwordx4 v134, s[20:21]
	s_mov_b32 m0, s57
	s_addc_u32 s1, s21, 0
	s_add_i32 s58, s35, 0x4000
	global_load_lds_dwordx4 v130, s[20:21]
	s_mov_b32 m0, s58
	s_add_i32 s59, s35, 0x6000
	global_load_lds_dwordx4 v134, s[0:1]
	s_mov_b32 m0, s59
	v_mov_b32_e32 v133, 0
	global_load_lds_dwordx4 v130, s[0:1]
	s_mov_b32 s98, s12
	s_mov_b32 s99, s4
	s_mov_b32 s100, s8
	v_mov_b32_e32 v240, v10
	v_mov_b32_e32 v241, v11
	v_mov_b32_e32 v242, v12
	v_mov_b32_e32 v243, v8
	v_mov_b32_e32 v244, v9

; __device__ __forceinline__ unsigned xb_ld(unsigned* p)              { return __hip_atomic_load(p, __ATOMIC_RELAXED, __HIP_MEMORY_SCOPE_AGENT); }
; __device__ __forceinline__ unsigned xb_add(unsigned* p, unsigned v) { return __hip_atomic_fetch_add(p, v, __ATOMIC_RELAXED, __HIP_MEMORY_SCOPE_AGENT); }
; #define XB_SPIN(cond, bar) do { unsigned _sp = 0; while (cond) { __builtin_amdgcn_s_sleep(1); \
;     if ((++_sp & 255u) == 0u) { if (xb_ld(&(bar)[XB_TMO])) break; if (_sp > XB_SPIN_CAP) { atomicAdd(&(bar)[XB_TMO], 1u); break; } } } } while (0)
; __device__ __forceinline__ void xcd_barrier(const XcdBarrier& b) {
;     ...
;         const unsigned old = xb_add(&bar[XB_XSUB(b.x)], 1u);
;         const unsigned gen = old / nloc;
;         if (old + 1u == (gen + 1u) * nloc) {
;             __builtin_amdgcn_fence(__ATOMIC_RELEASE, "agent");
;             asm volatile("s_waitcnt vmcnt(0)" ::: "memory");
;             const unsigned og = xb_add(&bar[XB_TOP], 1u);
;             const unsigned tg = og / nx;
;             if (og + 1u == (tg + 1u) * nx) xb_add(&bar[XB_TOPGEN], 1u);
;             else XB_SPIN(xb_ld(&bar[XB_TOPGEN]) == tg, bar);
;             __builtin_amdgcn_fence(__ATOMIC_ACQUIRE, "agent");
;             xb_add(&bar[XB_XGEN(b.x)], 1u);
;             asm volatile("s_waitcnt vmcnt(0)" ::: "memory");
.LBB0_264:
	s_andn2_saveexec_b64 s[8:9], s[8:9]
	s_cbranch_execz .LBB0_284
	s_mov_b64 s[8:9], exec
	v_readlane_b32 s3, v249, 48
	s_nop 3
	s_cmp_lg_u32 s3, 0
	s_cbranch_scc1 .LBB0_281
	buffer_wbl2 sc1
	s_waitcnt lgkmcnt(0)
	s_waitcnt vmcnt(0)
	v_mbcnt_lo_u32_b32 v1, s8, 0
	v_mbcnt_hi_u32_b32 v1, s9, v1
	v_cmp_eq_u32_e32 vcc, 0, v1
	s_and_saveexec_b64 s[10:11], vcc
	s_cbranch_execz .LBB0_267
	s_bcnt1_i32_b64 s3, s[8:9]
	v_mov_b32_e32 v2, 0x183000
	v_mov_b32_e32 v3, s3
	global_atomic_add v2, v2, v3, s[28:29] offset:1024 sc0
